# P11 epilogue: last-use residual (T2) loads carry the nt hint
# baseline (speedup 1.0000x reference)
;     __device__ __forceinline__ void piece(size_t row, int col, f32x4 v0, f32x4 v1, const f32x4 a0, const f32x4 a1, const f32x4 b0, const f32x4 b1, const f32x4 c0, const f32x4 c1,
;                                           float mean, float rstd, float& s, float& ss) const {
;     ...
;         if constexpr (RECOMP) { f32x4 r0, r1; unpack8(*(const u32x4*)(Tin + row * DM + col), r0, r1);
;             r0 = (r0 - mean) * rstd * a0 + b0; r1 = (r1 - mean) * rstd * a1 + b1; v0 = r0 * ALPHA + v0; v1 = r1 * ALPHA + v1;
;             if constexpr (MODE == 5) { v0 = v0 + c0; v1 = v1 + c1; } }
;         if constexpr (MODE == 4) { v0 = (v0 - a0 * mean) * rstd + b0; v1 = (v1 - a1 * mean) * rstd + b1;
; #pragma unroll
;             for (int e = 0; e < 4; ++e) { const float x = fmaxf(v0[e], 0.f), y = fmaxf(v1[e], 0.f); v0[e] = x * x; v1[e] = y * y; } }
;         if constexpr (PROD) {
; #pragma unroll
;             for (int e = 0; e < 4; ++e) { s += v0[e] + v1[e]; ss += v0[e] * v0[e] + v1[e] * v1[e]; } }
;     __device__ __forceinline__ void operator()(const f32x4 (&acc)[2][2][4][2], const Unit& u, int wr, int wc, int fr_, int fq_, LAS unsigned char* ldsx) const {
;     ...
;         const int colb = u.col0 + wc * 32 + 8 * fq;
;         const f32x4 z = (f32x4){0.f, 0.f, 0.f, 0.f};
;         f32x4 av[2][2], bv[2][2], cv[2][2];
; #pragma unroll
;         for (int bj = 0; bj < 2; ++bj)
; #pragma unroll
;             for (int n = 0; n < 2; ++n) { av[bj][n] = CONS ? *(const f32x4*)(va + colb + bj * HALF + 4 * n) : z; bv[bj][n] = CONS ? *(const f32x4*)(vb + colb + bj * HALF + 4 * n) : z;
;                                           cv[bj][n] = (MODE == 5) ? *(const f32x4*)(bias + colb + bj * HALF + 4 * n) : z; }
; #pragma unroll
;         EPI_FOR_ROWS {
;             const int rl = ai * HALF + wr * 64 + m * 16 + fr; const size_t row = (size_t)u.row0 + rl;
;             float mean = 0.f, rstd = 0.f; if constexpr (CONS) { const f32x2 st = X[rl]; mean = st.x; rstd = st.y; }
;             float s = 0.f, ss = 0.f;
; #pragma unroll
;             for (int bj = 0; bj < 2; ++bj) piece(row, colb + bj * HALF, acc[ai][bj][m][0], acc[ai][bj][m][1], av[bj][0], av[bj][1], bv[bj][0], bv[bj][1], cv[bj][0], cv[bj][1], mean, rstd, s, ss);
;             if constexpr (PROD) { s += __shfl_xor(s, 16); ss += __shfl_xor(ss, 16); s += __shfl_xor(s, 32); ss += __shfl_xor(ss, 32);
.LBB0_1480:
	v_mov_b32_e32 v82, v204
	v_mov_b32_e32 v80, v205
	s_cmp_eq_u32 s20, s8
	s_cselect_b32 s23, 0, 0x800
	s_add_i32 s21, s30, s43
	v_add_u32_e32 v198, s42, v82
	v_lshl_add_u32 v80, v80, 3, s21
	s_ashr_i32 s21, s20, 31
	v_ashrrev_i32_e32 v199, 31, v198
	v_lshl_add_u64 v[82:83], v[198:199], 0, s[20:21]
	v_ashrrev_i32_e32 v81, 31, v80
	v_lshlrev_b64 v[84:85], 11, v[82:83]
	v_lshl_add_u64 v[84:85], s[88:89], 0, v[84:85]
	v_lshlrev_b64 v[200:201], 1, v[80:81]
	v_lshl_add_u64 v[214:215], v[84:85], 0, v[200:201]
	v_readlane_b32 s64, v254, 3
	global_load_dwordx4 v[210:213], v[214:215], off
	v_readlane_b32 s76, v254, 15
	v_readlane_b32 s77, v254, 16
	v_readlane_b32 s78, v254, 17
	v_readlane_b32 s79, v254, 18
	s_mov_b64 s[16:17], s[76:77]
	v_lshlrev_b64 v[196:197], 2, v[80:81]
	s_mov_b64 s[18:19], s[78:79]
	v_lshl_add_u64 v[84:85], s[18:19], 0, v[196:197]
	v_lshl_add_u64 v[80:81], s[16:17], 0, v[196:197]
	global_load_dwordx4 v[116:119], v[84:85], off
	global_load_dwordx4 v[120:123], v[80:81], off
	global_load_dwordx4 v[112:115], v[80:81], off offset:16
	global_load_dwordx4 v[124:127], v[84:85], off offset:16
	v_lshl_add_u64 v[86:87], s[50:51], 0, v[196:197]
	global_load_dwordx4 v[108:111], v[86:87], off
	global_load_dwordx4 v[104:107], v[86:87], off offset:16
	s_add_i32 s23, s23, 0
	v_lshl_add_u32 v88, v198, 3, s23
	v_add_u32_e32 v199, 0x20000, v88
	ds_read2_b64 v[176:179], v199 offset1:16
	v_lshlrev_b64 v[216:217], 12, v[82:83]
	v_lshl_add_u64 v[216:217], s[56:57], 0, v[216:217]
	v_lshl_add_u64 v[216:217], v[216:217], 0, v[196:197]
	global_load_dwordx4 v[88:91], v[80:81], off offset:528
	global_load_dwordx4 v[96:99], v[80:81], off offset:512
	global_load_dwordx4 v[92:95], v[84:85], off offset:528
	global_load_dwordx4 v[100:103], v[84:85], off offset:512
	s_nop 0
	global_load_dwordx4 v[80:83], v[86:87], off offset:528
	s_nop 0
	global_load_dwordx4 v[84:87], v[86:87], off offset:512
	s_andn2_b64 vcc, exec, s[0:1]
	s_mov_b64 s[0:1], -1
	v_readlane_b32 s65, v254, 4
	v_readlane_b32 s66, v254, 5
	v_readlane_b32 s67, v254, 6
	v_readlane_b32 s68, v254, 7
	v_readlane_b32 s69, v254, 8
	v_readlane_b32 s70, v254, 9
	v_readlane_b32 s71, v254, 10
	v_readlane_b32 s72, v254, 11
	v_readlane_b32 s73, v254, 12
	v_readlane_b32 s74, v254, 13
	v_readlane_b32 s75, v254, 14
	global_load_dwordx4 v[218:221], v[214:215], off offset:256 nt
	v_add_u32_e32 v250, 0x10, v198
	v_ashrrev_i32_e32 v251, 31, v250
	v_lshl_add_u64 v[250:251], v[250:251], 0, s[20:21]
	v_lshlrev_b64 v[250:251], 11, v[250:251]
	v_lshl_add_u64 v[250:251], s[88:89], 0, v[250:251]
	v_lshl_add_u64 v[250:251], v[250:251], 0, v[200:201]
	global_load_dwordx4 v[222:225], v[250:251], off nt
	v_add_u32_e32 v250, 0x10, v198
	v_ashrrev_i32_e32 v251, 31, v250
	v_lshl_add_u64 v[250:251], v[250:251], 0, s[20:21]
	v_lshlrev_b64 v[250:251], 11, v[250:251]
	v_lshl_add_u64 v[250:251], s[88:89], 0, v[250:251]
	v_lshl_add_u64 v[250:251], v[250:251], 0, v[200:201]
	global_load_dwordx4 v[226:229], v[250:251], off offset:256 nt
	v_add_u32_e32 v250, 0x20, v198
	v_ashrrev_i32_e32 v251, 31, v250
	v_lshl_add_u64 v[250:251], v[250:251], 0, s[20:21]
	v_lshlrev_b64 v[250:251], 11, v[250:251]
	v_lshl_add_u64 v[250:251], s[88:89], 0, v[250:251]
	v_lshl_add_u64 v[250:251], v[250:251], 0, v[200:201]
	global_load_dwordx4 v[230:233], v[250:251], off nt
	v_add_u32_e32 v250, 0x20, v198
	v_ashrrev_i32_e32 v251, 31, v250
	v_lshl_add_u64 v[250:251], v[250:251], 0, s[20:21]
	v_lshlrev_b64 v[250:251], 11, v[250:251]
	v_lshl_add_u64 v[250:251], s[88:89], 0, v[250:251]
	v_lshl_add_u64 v[250:251], v[250:251], 0, v[200:201]
	global_load_dwordx4 v[234:237], v[250:251], off offset:256 nt
	ds_read2_b64 v[238:241], v199 offset0:32 offset1:48
	ds_read2_b64 v[242:245], v199 offset0:128 offset1:144
	ds_read2_b64 v[246:249], v199 offset0:160 offset1:176
	s_waitcnt vmcnt(5)
	v_pk_mul_f32 v[120:121], v[120:121], s[14:15] op_sel_hi:[1,0]
	v_pk_fma_f32 v[116:117], v[116:117], s[14:15], v[108:109] op_sel_hi:[1,0,1]
	v_pk_mul_f32 v[122:123], v[122:123], s[14:15] op_sel_hi:[1,0]
	v_pk_fma_f32 v[118:119], v[118:119], s[14:15], v[110:111] op_sel_hi:[1,0,1]
	v_pk_mul_f32 v[112:113], v[112:113], s[14:15] op_sel_hi:[1,0]
	v_pk_fma_f32 v[124:125], v[124:125], s[14:15], v[104:105] op_sel_hi:[1,0,1]
	v_pk_mul_f32 v[114:115], v[114:115], s[14:15] op_sel_hi:[1,0]
	v_pk_fma_f32 v[126:127], v[126:127], s[14:15], v[106:107] op_sel_hi:[1,0,1]
	v_pk_mul_f32 v[96:97], v[96:97], s[14:15] op_sel_hi:[1,0]
	v_pk_fma_f32 v[100:101], v[100:101], s[14:15], v[84:85] op_sel_hi:[1,0,1]
	v_pk_mul_f32 v[98:99], v[98:99], s[14:15] op_sel_hi:[1,0]
	v_pk_fma_f32 v[102:103], v[102:103], s[14:15], v[86:87] op_sel_hi:[1,0,1]
	v_pk_mul_f32 v[88:89], v[88:89], s[14:15] op_sel_hi:[1,0]
	v_pk_fma_f32 v[92:93], v[92:93], s[14:15], v[80:81] op_sel_hi:[1,0,1]
	v_pk_mul_f32 v[90:91], v[90:91], s[14:15] op_sel_hi:[1,0]
	v_pk_fma_f32 v[94:95], v[94:95], s[14:15], v[82:83] op_sel_hi:[1,0,1]
	v_mbcnt_lo_u32_b32 v110, -1, 0
	v_mbcnt_hi_u32_b32 v110, -1, v110
	v_xor_b32_e32 v111, 32, v110
	v_xor_b32_e32 v110, 16, v110
	v_lshlrev_b32_e32 v111, 2, v111
	v_lshlrev_b32_e32 v110, 2, v110
	v_lshlrev_b32_e32 v252, 5, v198
	v_mov_b32_e32 v108, s43
	v_lshrrev_b32_e32 v108, 2, v108
	v_add_u32_e32 v252, v252, v108
	v_add_u32_e32 v252, 0x21000, v252
	s_waitcnt lgkmcnt(0)
	s_waitcnt vmcnt(5)
; #define EPI_FOR_ROWS for (int ai = 0; ai < 2; ++ai) _Pragma("unroll") for (int m = 0; m < 4; ++m)
; __device__ __forceinline__ void unpack8(const u32x4 w, f32x4& a, f32x4& b) { a = (f32x4){bf_lo(w.x), bf_hi(w.x), bf_lo(w.y), bf_hi(w.y)}; b = (f32x4){bf_lo(w.z), bf_hi(w.z), bf_lo(w.w), bf_hi(w.w)}; }
;     __device__ __forceinline__ void piece(size_t row, int col, f32x4 v0, f32x4 v1, const f32x4 a0, const f32x4 a1, const f32x4 b0, const f32x4 b1, const f32x4 c0, const f32x4 c1,
;                                           float mean, float rstd, float& s, float& ss) const {
;     ...
;         if constexpr (RECOMP) { f32x4 r0, r1; unpack8(*(const u32x4*)(Tin + row * DM + col), r0, r1);
;             r0 = (r0 - mean) * rstd * a0 + b0; r1 = (r1 - mean) * rstd * a1 + b1; v0 = r0 * ALPHA + v0; v1 = r1 * ALPHA + v1;
;             if constexpr (MODE == 5) { v0 = v0 + c0; v1 = v1 + c1; } }
;     __device__ __forceinline__ void operator()(const f32x4 (&acc)[2][2][4][2], const Unit& u, int wr, int wc, int fr_, int fq_, LAS unsigned char* ldsx) const {
;     ...
;         EPI_FOR_ROWS {
;             const int rl = ai * HALF + wr * 64 + m * 16 + fr; const size_t row = (size_t)u.row0 + rl;
;             float mean = 0.f, rstd = 0.f; if constexpr (CONS) { const f32x2 st = X[rl]; mean = st.x; rstd = st.y; }
;             float s = 0.f, ss = 0.f;
; #pragma unroll
;             for (int bj = 0; bj < 2; ++bj) piece(row, colb + bj * HALF, acc[ai][bj][m][0], acc[ai][bj][m][1], av[bj][0], av[bj][1], bv[bj][0], bv[bj][1], cv[bj][0], cv[bj][1], mean, rstd, s, ss);
;             if constexpr (PROD) { s += __shfl_xor(s, 16); ss += __shfl_xor(ss, 16); s += __shfl_xor(s, 32); ss += __shfl_xor(ss, 32);
;                 if (fq == 0) st_out[row * 16 + (u.col0 >> 8) * 4 + wc] = (f32x2){s, ss}; }
;         }
	v_lshlrev_b32_e32 v80, 16, v210
	v_and_b32_e32 v81, 0xffff0000, v210
	v_lshlrev_b32_e32 v82, 16, v211
	v_and_b32_e32 v83, 0xffff0000, v211
	v_lshlrev_b32_e32 v84, 16, v212
	v_and_b32_e32 v85, 0xffff0000, v212
	v_lshlrev_b32_e32 v86, 16, v213
	v_and_b32_e32 v87, 0xffff0000, v213
	v_add_u32_e32 v250, 0x30, v198
	v_ashrrev_i32_e32 v251, 31, v250
	v_lshl_add_u64 v[250:251], v[250:251], 0, s[20:21]
	v_lshlrev_b64 v[250:251], 11, v[250:251]
	v_lshl_add_u64 v[250:251], s[88:89], 0, v[250:251]
	v_lshl_add_u64 v[250:251], v[250:251], 0, v[200:201]
	global_load_dwordx4 v[210:213], v[250:251], off nt
	v_pk_add_f32 v[80:81], v[80:81], v[176:177] op_sel_hi:[1,0] neg_lo:[0,1] neg_hi:[0,1]
	v_pk_mul_f32 v[80:81], v[176:177], v[80:81] op_sel:[1,0]
	v_pk_fma_f32 v[80:81], v[80:81], v[120:121], v[116:117]
	v_pk_add_f32 v[172:173], v[172:173], v[80:81]
	v_pk_add_f32 v[82:83], v[82:83], v[176:177] op_sel_hi:[1,0] neg_lo:[0,1] neg_hi:[0,1]
	v_pk_mul_f32 v[82:83], v[176:177], v[82:83] op_sel:[1,0]
	v_pk_fma_f32 v[82:83], v[82:83], v[122:123], v[118:119]
	v_pk_add_f32 v[174:175], v[174:175], v[82:83]
	v_pk_add_f32 v[84:85], v[84:85], v[176:177] op_sel_hi:[1,0] neg_lo:[0,1] neg_hi:[0,1]
	v_pk_mul_f32 v[84:85], v[176:177], v[84:85] op_sel:[1,0]
	v_pk_fma_f32 v[84:85], v[84:85], v[112:113], v[124:125]
	v_pk_add_f32 v[168:169], v[168:169], v[84:85]
	v_pk_add_f32 v[86:87], v[86:87], v[176:177] op_sel_hi:[1,0] neg_lo:[0,1] neg_hi:[0,1]
	v_pk_mul_f32 v[86:87], v[176:177], v[86:87] op_sel:[1,0]
	v_pk_fma_f32 v[86:87], v[86:87], v[114:115], v[126:127]
	v_pk_add_f32 v[170:171], v[170:171], v[86:87]
	v_pk_mul_f32 v[106:107], v[172:173], v[172:173]
	v_pk_add_f32 v[104:105], v[172:173], v[174:175]
	v_pk_fma_f32 v[106:107], v[174:175], v[174:175], v[106:107]
	v_pk_add_f32 v[104:105], v[104:105], v[168:169]
	v_pk_fma_f32 v[106:107], v[168:169], v[168:169], v[106:107]
	v_pk_add_f32 v[104:105], v[104:105], v[170:171]
	v_pk_fma_f32 v[106:107], v[170:171], v[170:171], v[106:107]
	s_waitcnt vmcnt(5)
	v_lshlrev_b32_e32 v80, 16, v218
	v_and_b32_e32 v81, 0xffff0000, v218
	v_lshlrev_b32_e32 v82, 16, v219
	v_and_b32_e32 v83, 0xffff0000, v219
	v_lshlrev_b32_e32 v84, 16, v220
	v_and_b32_e32 v85, 0xffff0000, v220
	v_lshlrev_b32_e32 v86, 16, v221
	v_and_b32_e32 v87, 0xffff0000, v221
	v_add_u32_e32 v250, 0x30, v198
	v_ashrrev_i32_e32 v251, 31, v250
	v_lshl_add_u64 v[250:251], v[250:251], 0, s[20:21]
	v_lshlrev_b64 v[250:251], 11, v[250:251]
	v_lshl_add_u64 v[250:251], s[88:89], 0, v[250:251]
	v_lshl_add_u64 v[250:251], v[250:251], 0, v[200:201]
	global_load_dwordx4 v[218:221], v[250:251], off offset:256 nt
	v_pk_add_f32 v[80:81], v[80:81], v[176:177] op_sel_hi:[1,0] neg_lo:[0,1] neg_hi:[0,1]
	v_pk_mul_f32 v[80:81], v[176:177], v[80:81] op_sel:[1,0]
	v_pk_fma_f32 v[80:81], v[80:81], v[96:97], v[100:101]
	v_pk_add_f32 v[164:165], v[164:165], v[80:81]
	v_pk_add_f32 v[82:83], v[82:83], v[176:177] op_sel_hi:[1,0] neg_lo:[0,1] neg_hi:[0,1]
	v_pk_mul_f32 v[82:83], v[176:177], v[82:83] op_sel:[1,0]
	v_pk_fma_f32 v[82:83], v[82:83], v[98:99], v[102:103]
	v_pk_add_f32 v[166:167], v[166:167], v[82:83]
	v_pk_add_f32 v[84:85], v[84:85], v[176:177] op_sel_hi:[1,0] neg_lo:[0,1] neg_hi:[0,1]
	v_pk_mul_f32 v[84:85], v[176:177], v[84:85] op_sel:[1,0]
	v_pk_fma_f32 v[84:85], v[84:85], v[88:89], v[92:93]
	v_pk_add_f32 v[160:161], v[160:161], v[84:85]
	v_pk_add_f32 v[86:87], v[86:87], v[176:177] op_sel_hi:[1,0] neg_lo:[0,1] neg_hi:[0,1]
	v_pk_mul_f32 v[86:87], v[176:177], v[86:87] op_sel:[1,0]
	v_pk_fma_f32 v[86:87], v[86:87], v[90:91], v[94:95]
	v_pk_add_f32 v[162:163], v[162:163], v[86:87]
	v_pk_add_f32 v[104:105], v[104:105], v[164:165]
	v_pk_fma_f32 v[106:107], v[164:165], v[164:165], v[106:107]
	v_pk_add_f32 v[104:105], v[104:105], v[166:167]
	v_pk_fma_f32 v[106:107], v[166:167], v[166:167], v[106:107]
	v_pk_add_f32 v[104:105], v[104:105], v[160:161]
	v_pk_fma_f32 v[106:107], v[160:161], v[160:161], v[106:107]
	v_pk_add_f32 v[104:105], v[104:105], v[162:163]
	v_pk_fma_f32 v[106:107], v[162:163], v[162:163], v[106:107]
	v_add_f32_e32 v108, v104, v105
	v_add_f32_e32 v109, v106, v107
	s_nop 0
	ds_bpermute_b32 v104, v110, v108
	ds_bpermute_b32 v105, v110, v109
	s_waitcnt lgkmcnt(0)
	v_pk_add_f32 v[108:109], v[108:109], v[104:105]
	s_nop 0
	ds_bpermute_b32 v104, v111, v108
	ds_bpermute_b32 v105, v111, v109
	s_waitcnt lgkmcnt(0)
	v_pk_add_f32 v[108:109], v[108:109], v[104:105]
	ds_write_b64 v252, v[108:109] offset:0
	s_waitcnt vmcnt(5)
	v_lshlrev_b32_e32 v80, 16, v222
	v_and_b32_e32 v81, 0xffff0000, v222
	v_lshlrev_b32_e32 v82, 16, v223
	v_and_b32_e32 v83, 0xffff0000, v223
	v_lshlrev_b32_e32 v84, 16, v224
	v_and_b32_e32 v85, 0xffff0000, v224
	v_lshlrev_b32_e32 v86, 16, v225
	v_and_b32_e32 v87, 0xffff0000, v225
	v_add_u32_e32 v250, 0x80, v198
	v_ashrrev_i32_e32 v251, 31, v250
	v_lshl_add_u64 v[250:251], v[250:251], 0, s[20:21]
	v_lshlrev_b64 v[250:251], 11, v[250:251]
	v_lshl_add_u64 v[250:251], s[88:89], 0, v[250:251]
	v_lshl_add_u64 v[250:251], v[250:251], 0, v[200:201]
	global_load_dwordx4 v[222:225], v[250:251], off nt
	v_pk_add_f32 v[80:81], v[80:81], v[178:179] op_sel_hi:[1,0] neg_lo:[0,1] neg_hi:[0,1]
	v_pk_mul_f32 v[80:81], v[178:179], v[80:81] op_sel:[1,0]
	v_pk_fma_f32 v[80:81], v[80:81], v[120:121], v[116:117]
	v_pk_add_f32 v[156:157], v[156:157], v[80:81]
	v_pk_add_f32 v[82:83], v[82:83], v[178:179] op_sel_hi:[1,0] neg_lo:[0,1] neg_hi:[0,1]
	v_pk_mul_f32 v[82:83], v[178:179], v[82:83] op_sel:[1,0]
	v_pk_fma_f32 v[82:83], v[82:83], v[122:123], v[118:119]
	v_pk_add_f32 v[158:159], v[158:159], v[82:83]
	v_pk_add_f32 v[84:85], v[84:85], v[178:179] op_sel_hi:[1,0] neg_lo:[0,1] neg_hi:[0,1]
	v_pk_mul_f32 v[84:85], v[178:179], v[84:85] op_sel:[1,0]
	v_pk_fma_f32 v[84:85], v[84:85], v[112:113], v[124:125]
	v_pk_add_f32 v[152:153], v[152:153], v[84:85]
	v_pk_add_f32 v[86:87], v[86:87], v[178:179] op_sel_hi:[1,0] neg_lo:[0,1] neg_hi:[0,1]
	v_pk_mul_f32 v[86:87], v[178:179], v[86:87] op_sel:[1,0]
	v_pk_fma_f32 v[86:87], v[86:87], v[114:115], v[126:127]
	v_pk_add_f32 v[154:155], v[154:155], v[86:87]
	v_pk_mul_f32 v[106:107], v[156:157], v[156:157]
	v_pk_add_f32 v[104:105], v[156:157], v[158:159]
	v_pk_fma_f32 v[106:107], v[158:159], v[158:159], v[106:107]
	v_pk_add_f32 v[104:105], v[104:105], v[152:153]
	v_pk_fma_f32 v[106:107], v[152:153], v[152:153], v[106:107]
	v_pk_add_f32 v[104:105], v[104:105], v[154:155]
	v_pk_fma_f32 v[106:107], v[154:155], v[154:155], v[106:107]
	s_waitcnt vmcnt(5)
; #define EPI_FOR_ROWS for (int ai = 0; ai < 2; ++ai) _Pragma("unroll") for (int m = 0; m < 4; ++m)
; __device__ __forceinline__ void unpack8(const u32x4 w, f32x4& a, f32x4& b) { a = (f32x4){bf_lo(w.x), bf_hi(w.x), bf_lo(w.y), bf_hi(w.y)}; b = (f32x4){bf_lo(w.z), bf_hi(w.z), bf_lo(w.w), bf_hi(w.w)}; }
;     __device__ __forceinline__ void piece(size_t row, int col, f32x4 v0, f32x4 v1, const f32x4 a0, const f32x4 a1, const f32x4 b0, const f32x4 b1, const f32x4 c0, const f32x4 c1,
;                                           float mean, float rstd, float& s, float& ss) const {
;     ...
;         if constexpr (RECOMP) { f32x4 r0, r1; unpack8(*(const u32x4*)(Tin + row * DM + col), r0, r1);
;             r0 = (r0 - mean) * rstd * a0 + b0; r1 = (r1 - mean) * rstd * a1 + b1; v0 = r0 * ALPHA + v0; v1 = r1 * ALPHA + v1;
;             if constexpr (MODE == 5) { v0 = v0 + c0; v1 = v1 + c1; } }
;     __device__ __forceinline__ void operator()(const f32x4 (&acc)[2][2][4][2], const Unit& u, int wr, int wc, int fr_, int fq_, LAS unsigned char* ldsx) const {
;     ...
;         EPI_FOR_ROWS {
;             const int rl = ai * HALF + wr * 64 + m * 16 + fr; const size_t row = (size_t)u.row0 + rl;
;             float mean = 0.f, rstd = 0.f; if constexpr (CONS) { const f32x2 st = X[rl]; mean = st.x; rstd = st.y; }
;             float s = 0.f, ss = 0.f;
; #pragma unroll
;             for (int bj = 0; bj < 2; ++bj) piece(row, colb + bj * HALF, acc[ai][bj][m][0], acc[ai][bj][m][1], av[bj][0], av[bj][1], bv[bj][0], bv[bj][1], cv[bj][0], cv[bj][1], mean, rstd, s, ss);
;             if constexpr (PROD) { s += __shfl_xor(s, 16); ss += __shfl_xor(ss, 16); s += __shfl_xor(s, 32); ss += __shfl_xor(ss, 32);
;                 if (fq == 0) st_out[row * 16 + (u.col0 >> 8) * 4 + wc] = (f32x2){s, ss}; }
;         }
	v_lshlrev_b32_e32 v80, 16, v226
	v_and_b32_e32 v81, 0xffff0000, v226
	v_lshlrev_b32_e32 v82, 16, v227
	v_and_b32_e32 v83, 0xffff0000, v227
	v_lshlrev_b32_e32 v84, 16, v228
	v_and_b32_e32 v85, 0xffff0000, v228
	v_lshlrev_b32_e32 v86, 16, v229
	v_and_b32_e32 v87, 0xffff0000, v229
	v_add_u32_e32 v250, 0x80, v198
	v_ashrrev_i32_e32 v251, 31, v250
	v_lshl_add_u64 v[250:251], v[250:251], 0, s[20:21]
	v_lshlrev_b64 v[250:251], 11, v[250:251]
	v_lshl_add_u64 v[250:251], s[88:89], 0, v[250:251]
	v_lshl_add_u64 v[250:251], v[250:251], 0, v[200:201]
	global_load_dwordx4 v[226:229], v[250:251], off offset:256 nt
	v_pk_add_f32 v[80:81], v[80:81], v[178:179] op_sel_hi:[1,0] neg_lo:[0,1] neg_hi:[0,1]
	v_pk_mul_f32 v[80:81], v[178:179], v[80:81] op_sel:[1,0]
	v_pk_fma_f32 v[80:81], v[80:81], v[96:97], v[100:101]
	v_pk_add_f32 v[148:149], v[148:149], v[80:81]
	v_pk_add_f32 v[82:83], v[82:83], v[178:179] op_sel_hi:[1,0] neg_lo:[0,1] neg_hi:[0,1]
	v_pk_mul_f32 v[82:83], v[178:179], v[82:83] op_sel:[1,0]
	v_pk_fma_f32 v[82:83], v[82:83], v[98:99], v[102:103]
	v_pk_add_f32 v[150:151], v[150:151], v[82:83]
	v_pk_add_f32 v[84:85], v[84:85], v[178:179] op_sel_hi:[1,0] neg_lo:[0,1] neg_hi:[0,1]
	v_pk_mul_f32 v[84:85], v[178:179], v[84:85] op_sel:[1,0]
	v_pk_fma_f32 v[84:85], v[84:85], v[88:89], v[92:93]
	v_pk_add_f32 v[144:145], v[144:145], v[84:85]
	v_pk_add_f32 v[86:87], v[86:87], v[178:179] op_sel_hi:[1,0] neg_lo:[0,1] neg_hi:[0,1]
	v_pk_mul_f32 v[86:87], v[178:179], v[86:87] op_sel:[1,0]
	v_pk_fma_f32 v[86:87], v[86:87], v[90:91], v[94:95]
	v_pk_add_f32 v[146:147], v[146:147], v[86:87]
	v_pk_add_f32 v[104:105], v[104:105], v[148:149]
	v_pk_fma_f32 v[106:107], v[148:149], v[148:149], v[106:107]
	v_pk_add_f32 v[104:105], v[104:105], v[150:151]
	v_pk_fma_f32 v[106:107], v[150:151], v[150:151], v[106:107]
	v_pk_add_f32 v[104:105], v[104:105], v[144:145]
	v_pk_fma_f32 v[106:107], v[144:145], v[144:145], v[106:107]
	v_pk_add_f32 v[104:105], v[104:105], v[146:147]
	v_pk_fma_f32 v[106:107], v[146:147], v[146:147], v[106:107]
	v_add_f32_e32 v108, v104, v105
	v_add_f32_e32 v109, v106, v107
	s_nop 0
	ds_bpermute_b32 v104, v110, v108
	ds_bpermute_b32 v105, v110, v109
	s_waitcnt lgkmcnt(0)
	v_pk_add_f32 v[108:109], v[108:109], v[104:105]
	s_nop 0
	ds_bpermute_b32 v104, v111, v108
	ds_bpermute_b32 v105, v111, v109
	s_waitcnt lgkmcnt(0)
	v_pk_add_f32 v[108:109], v[108:109], v[104:105]
	ds_write_b64 v252, v[108:109] offset:512
	s_waitcnt vmcnt(5)
	v_lshlrev_b32_e32 v80, 16, v230
	v_and_b32_e32 v81, 0xffff0000, v230
	v_lshlrev_b32_e32 v82, 16, v231
	v_and_b32_e32 v83, 0xffff0000, v231
	v_lshlrev_b32_e32 v84, 16, v232
	v_and_b32_e32 v85, 0xffff0000, v232
	v_lshlrev_b32_e32 v86, 16, v233
	v_and_b32_e32 v87, 0xffff0000, v233
	v_add_u32_e32 v250, 0x90, v198
	v_ashrrev_i32_e32 v251, 31, v250
	v_lshl_add_u64 v[250:251], v[250:251], 0, s[20:21]
	v_lshlrev_b64 v[250:251], 11, v[250:251]
	v_lshl_add_u64 v[250:251], s[88:89], 0, v[250:251]
	v_lshl_add_u64 v[250:251], v[250:251], 0, v[200:201]
	global_load_dwordx4 v[230:233], v[250:251], off nt
	v_pk_add_f32 v[80:81], v[80:81], v[238:239] op_sel_hi:[1,0] neg_lo:[0,1] neg_hi:[0,1]
	v_pk_mul_f32 v[80:81], v[238:239], v[80:81] op_sel:[1,0]
	v_pk_fma_f32 v[80:81], v[80:81], v[120:121], v[116:117]
	v_pk_add_f32 v[140:141], v[140:141], v[80:81]
	v_pk_add_f32 v[82:83], v[82:83], v[238:239] op_sel_hi:[1,0] neg_lo:[0,1] neg_hi:[0,1]
	v_pk_mul_f32 v[82:83], v[238:239], v[82:83] op_sel:[1,0]
	v_pk_fma_f32 v[82:83], v[82:83], v[122:123], v[118:119]
	v_pk_add_f32 v[142:143], v[142:143], v[82:83]
	v_pk_add_f32 v[84:85], v[84:85], v[238:239] op_sel_hi:[1,0] neg_lo:[0,1] neg_hi:[0,1]
	v_pk_mul_f32 v[84:85], v[238:239], v[84:85] op_sel:[1,0]
	v_pk_fma_f32 v[84:85], v[84:85], v[112:113], v[124:125]
	v_pk_add_f32 v[136:137], v[136:137], v[84:85]
	v_pk_add_f32 v[86:87], v[86:87], v[238:239] op_sel_hi:[1,0] neg_lo:[0,1] neg_hi:[0,1]
	v_pk_mul_f32 v[86:87], v[238:239], v[86:87] op_sel:[1,0]
	v_pk_fma_f32 v[86:87], v[86:87], v[114:115], v[126:127]
	v_pk_add_f32 v[138:139], v[138:139], v[86:87]
	v_pk_mul_f32 v[106:107], v[140:141], v[140:141]
	v_pk_add_f32 v[104:105], v[140:141], v[142:143]
	v_pk_fma_f32 v[106:107], v[142:143], v[142:143], v[106:107]
	v_pk_add_f32 v[104:105], v[104:105], v[136:137]
	v_pk_fma_f32 v[106:107], v[136:137], v[136:137], v[106:107]
	v_pk_add_f32 v[104:105], v[104:105], v[138:139]
	v_pk_fma_f32 v[106:107], v[138:139], v[138:139], v[106:107]
	s_waitcnt vmcnt(5)
	v_lshlrev_b32_e32 v80, 16, v234
	v_and_b32_e32 v81, 0xffff0000, v234
	v_lshlrev_b32_e32 v82, 16, v235
	v_and_b32_e32 v83, 0xffff0000, v235
	v_lshlrev_b32_e32 v84, 16, v236
	v_and_b32_e32 v85, 0xffff0000, v236
	v_lshlrev_b32_e32 v86, 16, v237
	v_and_b32_e32 v87, 0xffff0000, v237
	v_add_u32_e32 v250, 0x90, v198
	v_ashrrev_i32_e32 v251, 31, v250
	v_lshl_add_u64 v[250:251], v[250:251], 0, s[20:21]
	v_lshlrev_b64 v[250:251], 11, v[250:251]
	v_lshl_add_u64 v[250:251], s[88:89], 0, v[250:251]
	v_lshl_add_u64 v[250:251], v[250:251], 0, v[200:201]
	global_load_dwordx4 v[234:237], v[250:251], off offset:256 nt
	v_pk_add_f32 v[80:81], v[80:81], v[238:239] op_sel_hi:[1,0] neg_lo:[0,1] neg_hi:[0,1]
	v_pk_mul_f32 v[80:81], v[238:239], v[80:81] op_sel:[1,0]
	v_pk_fma_f32 v[80:81], v[80:81], v[96:97], v[100:101]
	v_pk_add_f32 v[132:133], v[132:133], v[80:81]
	v_pk_add_f32 v[82:83], v[82:83], v[238:239] op_sel_hi:[1,0] neg_lo:[0,1] neg_hi:[0,1]
	v_pk_mul_f32 v[82:83], v[238:239], v[82:83] op_sel:[1,0]
	v_pk_fma_f32 v[82:83], v[82:83], v[98:99], v[102:103]
	v_pk_add_f32 v[134:135], v[134:135], v[82:83]
	v_pk_add_f32 v[84:85], v[84:85], v[238:239] op_sel_hi:[1,0] neg_lo:[0,1] neg_hi:[0,1]
	v_pk_mul_f32 v[84:85], v[238:239], v[84:85] op_sel:[1,0]
	v_pk_fma_f32 v[84:85], v[84:85], v[88:89], v[92:93]
	v_pk_add_f32 v[128:129], v[128:129], v[84:85]
	v_pk_add_f32 v[86:87], v[86:87], v[238:239] op_sel_hi:[1,0] neg_lo:[0,1] neg_hi:[0,1]
	v_pk_mul_f32 v[86:87], v[238:239], v[86:87] op_sel:[1,0]
	v_pk_fma_f32 v[86:87], v[86:87], v[90:91], v[94:95]
	v_pk_add_f32 v[130:131], v[130:131], v[86:87]
	v_pk_add_f32 v[104:105], v[104:105], v[132:133]
	v_pk_fma_f32 v[106:107], v[132:133], v[132:133], v[106:107]
	v_pk_add_f32 v[104:105], v[104:105], v[134:135]
	v_pk_fma_f32 v[106:107], v[134:135], v[134:135], v[106:107]
	v_pk_add_f32 v[104:105], v[104:105], v[128:129]
	v_pk_fma_f32 v[106:107], v[128:129], v[128:129], v[106:107]
	v_pk_add_f32 v[104:105], v[104:105], v[130:131]
	v_pk_fma_f32 v[106:107], v[130:131], v[130:131], v[106:107]
	v_add_f32_e32 v108, v104, v105
	v_add_f32_e32 v109, v106, v107
	s_nop 0
	ds_bpermute_b32 v104, v110, v108
	ds_bpermute_b32 v105, v110, v109
	s_waitcnt lgkmcnt(0)
; #define EPI_FOR_ROWS for (int ai = 0; ai < 2; ++ai) _Pragma("unroll") for (int m = 0; m < 4; ++m)
; __device__ __forceinline__ void unpack8(const u32x4 w, f32x4& a, f32x4& b) { a = (f32x4){bf_lo(w.x), bf_hi(w.x), bf_lo(w.y), bf_hi(w.y)}; b = (f32x4){bf_lo(w.z), bf_hi(w.z), bf_lo(w.w), bf_hi(w.w)}; }
;     __device__ __forceinline__ void piece(size_t row, int col, f32x4 v0, f32x4 v1, const f32x4 a0, const f32x4 a1, const f32x4 b0, const f32x4 b1, const f32x4 c0, const f32x4 c1,
;                                           float mean, float rstd, float& s, float& ss) const {
;     ...
;         if constexpr (RECOMP) { f32x4 r0, r1; unpack8(*(const u32x4*)(Tin + row * DM + col), r0, r1);
;             r0 = (r0 - mean) * rstd * a0 + b0; r1 = (r1 - mean) * rstd * a1 + b1; v0 = r0 * ALPHA + v0; v1 = r1 * ALPHA + v1;
;             if constexpr (MODE == 5) { v0 = v0 + c0; v1 = v1 + c1; } }
;     __device__ __forceinline__ void operator()(const f32x4 (&acc)[2][2][4][2], const Unit& u, int wr, int wc, int fr_, int fq_, LAS unsigned char* ldsx) const {
;     ...
;         EPI_FOR_ROWS {
;             const int rl = ai * HALF + wr * 64 + m * 16 + fr; const size_t row = (size_t)u.row0 + rl;
;             float mean = 0.f, rstd = 0.f; if constexpr (CONS) { const f32x2 st = X[rl]; mean = st.x; rstd = st.y; }
;             float s = 0.f, ss = 0.f;
; #pragma unroll
;             for (int bj = 0; bj < 2; ++bj) piece(row, colb + bj * HALF, acc[ai][bj][m][0], acc[ai][bj][m][1], av[bj][0], av[bj][1], bv[bj][0], bv[bj][1], cv[bj][0], cv[bj][1], mean, rstd, s, ss);
;             if constexpr (PROD) { s += __shfl_xor(s, 16); ss += __shfl_xor(ss, 16); s += __shfl_xor(s, 32); ss += __shfl_xor(ss, 32);
;                 if (fq == 0) st_out[row * 16 + (u.col0 >> 8) * 4 + wc] = (f32x2){s, ss}; }
;         }
	v_pk_add_f32 v[108:109], v[108:109], v[104:105]
	s_nop 0
	ds_bpermute_b32 v104, v111, v108
	ds_bpermute_b32 v105, v111, v109
	s_waitcnt lgkmcnt(0)
	v_pk_add_f32 v[108:109], v[108:109], v[104:105]
	ds_write_b64 v252, v[108:109] offset:1024
	s_waitcnt vmcnt(5)
	v_lshlrev_b32_e32 v80, 16, v210
	v_and_b32_e32 v81, 0xffff0000, v210
	v_lshlrev_b32_e32 v82, 16, v211
	v_and_b32_e32 v83, 0xffff0000, v211
	v_lshlrev_b32_e32 v84, 16, v212
	v_and_b32_e32 v85, 0xffff0000, v212
	v_lshlrev_b32_e32 v86, 16, v213
	v_and_b32_e32 v87, 0xffff0000, v213
	v_add_u32_e32 v250, 0xa0, v198
	v_ashrrev_i32_e32 v251, 31, v250
	v_lshl_add_u64 v[250:251], v[250:251], 0, s[20:21]
	v_lshlrev_b64 v[250:251], 11, v[250:251]
	v_lshl_add_u64 v[250:251], s[88:89], 0, v[250:251]
	v_lshl_add_u64 v[250:251], v[250:251], 0, v[200:201]
	global_load_dwordx4 v[210:213], v[250:251], off nt
	v_pk_add_f32 v[80:81], v[80:81], v[240:241] op_sel_hi:[1,0] neg_lo:[0,1] neg_hi:[0,1]
	v_pk_mul_f32 v[80:81], v[240:241], v[80:81] op_sel:[1,0]
	v_pk_fma_f32 v[80:81], v[80:81], v[120:121], v[116:117]
	v_pk_add_f32 v[76:77], v[76:77], v[80:81]
	v_pk_add_f32 v[82:83], v[82:83], v[240:241] op_sel_hi:[1,0] neg_lo:[0,1] neg_hi:[0,1]
	v_pk_mul_f32 v[82:83], v[240:241], v[82:83] op_sel:[1,0]
	v_pk_fma_f32 v[82:83], v[82:83], v[122:123], v[118:119]
	v_pk_add_f32 v[78:79], v[78:79], v[82:83]
	v_pk_add_f32 v[84:85], v[84:85], v[240:241] op_sel_hi:[1,0] neg_lo:[0,1] neg_hi:[0,1]
	v_pk_mul_f32 v[84:85], v[240:241], v[84:85] op_sel:[1,0]
	v_pk_fma_f32 v[84:85], v[84:85], v[112:113], v[124:125]
	v_pk_add_f32 v[72:73], v[72:73], v[84:85]
	v_pk_add_f32 v[86:87], v[86:87], v[240:241] op_sel_hi:[1,0] neg_lo:[0,1] neg_hi:[0,1]
	v_pk_mul_f32 v[86:87], v[240:241], v[86:87] op_sel:[1,0]
	v_pk_fma_f32 v[86:87], v[86:87], v[114:115], v[126:127]
	v_pk_add_f32 v[74:75], v[74:75], v[86:87]
	v_pk_mul_f32 v[106:107], v[76:77], v[76:77]
	v_pk_add_f32 v[104:105], v[76:77], v[78:79]
	v_pk_fma_f32 v[106:107], v[78:79], v[78:79], v[106:107]
	v_pk_add_f32 v[104:105], v[104:105], v[72:73]
	v_pk_fma_f32 v[106:107], v[72:73], v[72:73], v[106:107]
	v_pk_add_f32 v[104:105], v[104:105], v[74:75]
	v_pk_fma_f32 v[106:107], v[74:75], v[74:75], v[106:107]
	s_waitcnt vmcnt(5)
	v_lshlrev_b32_e32 v80, 16, v218
	v_and_b32_e32 v81, 0xffff0000, v218
	v_lshlrev_b32_e32 v82, 16, v219
	v_and_b32_e32 v83, 0xffff0000, v219
	v_lshlrev_b32_e32 v84, 16, v220
	v_and_b32_e32 v85, 0xffff0000, v220
	v_lshlrev_b32_e32 v86, 16, v221
	v_and_b32_e32 v87, 0xffff0000, v221
	v_add_u32_e32 v250, 0xa0, v198
	v_ashrrev_i32_e32 v251, 31, v250
	v_lshl_add_u64 v[250:251], v[250:251], 0, s[20:21]
	v_lshlrev_b64 v[250:251], 11, v[250:251]
	v_lshl_add_u64 v[250:251], s[88:89], 0, v[250:251]
	v_lshl_add_u64 v[250:251], v[250:251], 0, v[200:201]
	global_load_dwordx4 v[218:221], v[250:251], off offset:256 nt
	v_pk_add_f32 v[80:81], v[80:81], v[240:241] op_sel_hi:[1,0] neg_lo:[0,1] neg_hi:[0,1]
	v_pk_mul_f32 v[80:81], v[240:241], v[80:81] op_sel:[1,0]
	v_pk_fma_f32 v[80:81], v[80:81], v[96:97], v[100:101]
	v_pk_add_f32 v[68:69], v[68:69], v[80:81]
	v_pk_add_f32 v[82:83], v[82:83], v[240:241] op_sel_hi:[1,0] neg_lo:[0,1] neg_hi:[0,1]
	v_pk_mul_f32 v[82:83], v[240:241], v[82:83] op_sel:[1,0]
	v_pk_fma_f32 v[82:83], v[82:83], v[98:99], v[102:103]
	v_pk_add_f32 v[70:71], v[70:71], v[82:83]
	v_pk_add_f32 v[84:85], v[84:85], v[240:241] op_sel_hi:[1,0] neg_lo:[0,1] neg_hi:[0,1]
	v_pk_mul_f32 v[84:85], v[240:241], v[84:85] op_sel:[1,0]
	v_pk_fma_f32 v[84:85], v[84:85], v[88:89], v[92:93]
	v_pk_add_f32 v[64:65], v[64:65], v[84:85]
	v_pk_add_f32 v[86:87], v[86:87], v[240:241] op_sel_hi:[1,0] neg_lo:[0,1] neg_hi:[0,1]
	v_pk_mul_f32 v[86:87], v[240:241], v[86:87] op_sel:[1,0]
	v_pk_fma_f32 v[86:87], v[86:87], v[90:91], v[94:95]
	v_pk_add_f32 v[66:67], v[66:67], v[86:87]
	v_pk_add_f32 v[104:105], v[104:105], v[68:69]
	v_pk_fma_f32 v[106:107], v[68:69], v[68:69], v[106:107]
	v_pk_add_f32 v[104:105], v[104:105], v[70:71]
	v_pk_fma_f32 v[106:107], v[70:71], v[70:71], v[106:107]
	v_pk_add_f32 v[104:105], v[104:105], v[64:65]
	v_pk_fma_f32 v[106:107], v[64:65], v[64:65], v[106:107]
	v_pk_add_f32 v[104:105], v[104:105], v[66:67]
	v_pk_fma_f32 v[106:107], v[66:67], v[66:67], v[106:107]
	v_add_f32_e32 v108, v104, v105
	v_add_f32_e32 v109, v106, v107
	s_nop 0
	ds_bpermute_b32 v104, v110, v108
	ds_bpermute_b32 v105, v110, v109
	s_waitcnt lgkmcnt(0)
	v_pk_add_f32 v[108:109], v[108:109], v[104:105]
	s_nop 0
	ds_bpermute_b32 v104, v111, v108
	ds_bpermute_b32 v105, v111, v109
	s_waitcnt lgkmcnt(0)
	v_pk_add_f32 v[108:109], v[108:109], v[104:105]
	ds_write_b64 v252, v[108:109] offset:1536
	s_waitcnt vmcnt(5)
	v_lshlrev_b32_e32 v80, 16, v222
	v_and_b32_e32 v81, 0xffff0000, v222
	v_lshlrev_b32_e32 v82, 16, v223
	v_and_b32_e32 v83, 0xffff0000, v223
	v_lshlrev_b32_e32 v84, 16, v224
	v_and_b32_e32 v85, 0xffff0000, v224
	v_lshlrev_b32_e32 v86, 16, v225
	v_and_b32_e32 v87, 0xffff0000, v225
	v_add_u32_e32 v250, 0xb0, v198
	v_ashrrev_i32_e32 v251, 31, v250
	v_lshl_add_u64 v[250:251], v[250:251], 0, s[20:21]
	v_lshlrev_b64 v[250:251], 11, v[250:251]
	v_lshl_add_u64 v[250:251], s[88:89], 0, v[250:251]
	v_lshl_add_u64 v[250:251], v[250:251], 0, v[200:201]
	global_load_dwordx4 v[222:225], v[250:251], off nt
	v_pk_add_f32 v[80:81], v[80:81], v[242:243] op_sel_hi:[1,0] neg_lo:[0,1] neg_hi:[0,1]
	v_pk_mul_f32 v[80:81], v[242:243], v[80:81] op_sel:[1,0]
	v_pk_fma_f32 v[80:81], v[80:81], v[120:121], v[116:117]
	v_pk_add_f32 v[60:61], v[60:61], v[80:81]
	v_pk_add_f32 v[82:83], v[82:83], v[242:243] op_sel_hi:[1,0] neg_lo:[0,1] neg_hi:[0,1]
	v_pk_mul_f32 v[82:83], v[242:243], v[82:83] op_sel:[1,0]
	v_pk_fma_f32 v[82:83], v[82:83], v[122:123], v[118:119]
	v_pk_add_f32 v[62:63], v[62:63], v[82:83]
	v_pk_add_f32 v[84:85], v[84:85], v[242:243] op_sel_hi:[1,0] neg_lo:[0,1] neg_hi:[0,1]
	v_pk_mul_f32 v[84:85], v[242:243], v[84:85] op_sel:[1,0]
	v_pk_fma_f32 v[84:85], v[84:85], v[112:113], v[124:125]
	v_pk_add_f32 v[56:57], v[56:57], v[84:85]
	v_pk_add_f32 v[86:87], v[86:87], v[242:243] op_sel_hi:[1,0] neg_lo:[0,1] neg_hi:[0,1]
	v_pk_mul_f32 v[86:87], v[242:243], v[86:87] op_sel:[1,0]
	v_pk_fma_f32 v[86:87], v[86:87], v[114:115], v[126:127]
	v_pk_add_f32 v[58:59], v[58:59], v[86:87]
	v_pk_mul_f32 v[106:107], v[60:61], v[60:61]
	v_pk_add_f32 v[104:105], v[60:61], v[62:63]
	v_pk_fma_f32 v[106:107], v[62:63], v[62:63], v[106:107]
	v_pk_add_f32 v[104:105], v[104:105], v[56:57]
	v_pk_fma_f32 v[106:107], v[56:57], v[56:57], v[106:107]
	v_pk_add_f32 v[104:105], v[104:105], v[58:59]
	v_pk_fma_f32 v[106:107], v[58:59], v[58:59], v[106:107]
	s_waitcnt vmcnt(5)
; #define EPI_FOR_ROWS for (int ai = 0; ai < 2; ++ai) _Pragma("unroll") for (int m = 0; m < 4; ++m)
; __device__ __forceinline__ void unpack8(const u32x4 w, f32x4& a, f32x4& b) { a = (f32x4){bf_lo(w.x), bf_hi(w.x), bf_lo(w.y), bf_hi(w.y)}; b = (f32x4){bf_lo(w.z), bf_hi(w.z), bf_lo(w.w), bf_hi(w.w)}; }
;     __device__ __forceinline__ void piece(size_t row, int col, f32x4 v0, f32x4 v1, const f32x4 a0, const f32x4 a1, const f32x4 b0, const f32x4 b1, const f32x4 c0, const f32x4 c1,
;                                           float mean, float rstd, float& s, float& ss) const {
;     ...
;         if constexpr (RECOMP) { f32x4 r0, r1; unpack8(*(const u32x4*)(Tin + row * DM + col), r0, r1);
;             r0 = (r0 - mean) * rstd * a0 + b0; r1 = (r1 - mean) * rstd * a1 + b1; v0 = r0 * ALPHA + v0; v1 = r1 * ALPHA + v1;
;             if constexpr (MODE == 5) { v0 = v0 + c0; v1 = v1 + c1; } }
;     __device__ __forceinline__ void operator()(const f32x4 (&acc)[2][2][4][2], const Unit& u, int wr, int wc, int fr_, int fq_, LAS unsigned char* ldsx) const {
;     ...
;         EPI_FOR_ROWS {
;             const int rl = ai * HALF + wr * 64 + m * 16 + fr; const size_t row = (size_t)u.row0 + rl;
;             float mean = 0.f, rstd = 0.f; if constexpr (CONS) { const f32x2 st = X[rl]; mean = st.x; rstd = st.y; }
;             float s = 0.f, ss = 0.f;
; #pragma unroll
;             for (int bj = 0; bj < 2; ++bj) piece(row, colb + bj * HALF, acc[ai][bj][m][0], acc[ai][bj][m][1], av[bj][0], av[bj][1], bv[bj][0], bv[bj][1], cv[bj][0], cv[bj][1], mean, rstd, s, ss);
;             if constexpr (PROD) { s += __shfl_xor(s, 16); ss += __shfl_xor(ss, 16); s += __shfl_xor(s, 32); ss += __shfl_xor(ss, 32);
;                 if (fq == 0) st_out[row * 16 + (u.col0 >> 8) * 4 + wc] = (f32x2){s, ss}; }
;         }
	v_lshlrev_b32_e32 v80, 16, v226
	v_and_b32_e32 v81, 0xffff0000, v226
	v_lshlrev_b32_e32 v82, 16, v227
	v_and_b32_e32 v83, 0xffff0000, v227
	v_lshlrev_b32_e32 v84, 16, v228
	v_and_b32_e32 v85, 0xffff0000, v228
	v_lshlrev_b32_e32 v86, 16, v229
	v_and_b32_e32 v87, 0xffff0000, v229
	v_add_u32_e32 v250, 0xb0, v198
	v_ashrrev_i32_e32 v251, 31, v250
	v_lshl_add_u64 v[250:251], v[250:251], 0, s[20:21]
	v_lshlrev_b64 v[250:251], 11, v[250:251]
	v_lshl_add_u64 v[250:251], s[88:89], 0, v[250:251]
	v_lshl_add_u64 v[250:251], v[250:251], 0, v[200:201]
	global_load_dwordx4 v[226:229], v[250:251], off offset:256 nt
	v_pk_add_f32 v[80:81], v[80:81], v[242:243] op_sel_hi:[1,0] neg_lo:[0,1] neg_hi:[0,1]
	v_pk_mul_f32 v[80:81], v[242:243], v[80:81] op_sel:[1,0]
	v_pk_fma_f32 v[80:81], v[80:81], v[96:97], v[100:101]
	v_pk_add_f32 v[52:53], v[52:53], v[80:81]
	v_pk_add_f32 v[82:83], v[82:83], v[242:243] op_sel_hi:[1,0] neg_lo:[0,1] neg_hi:[0,1]
	v_pk_mul_f32 v[82:83], v[242:243], v[82:83] op_sel:[1,0]
	v_pk_fma_f32 v[82:83], v[82:83], v[98:99], v[102:103]
	v_pk_add_f32 v[54:55], v[54:55], v[82:83]
	v_pk_add_f32 v[84:85], v[84:85], v[242:243] op_sel_hi:[1,0] neg_lo:[0,1] neg_hi:[0,1]
	v_pk_mul_f32 v[84:85], v[242:243], v[84:85] op_sel:[1,0]
	v_pk_fma_f32 v[84:85], v[84:85], v[88:89], v[92:93]
	v_pk_add_f32 v[48:49], v[48:49], v[84:85]
	v_pk_add_f32 v[86:87], v[86:87], v[242:243] op_sel_hi:[1,0] neg_lo:[0,1] neg_hi:[0,1]
	v_pk_mul_f32 v[86:87], v[242:243], v[86:87] op_sel:[1,0]
	v_pk_fma_f32 v[86:87], v[86:87], v[90:91], v[94:95]
	v_pk_add_f32 v[50:51], v[50:51], v[86:87]
	v_pk_add_f32 v[104:105], v[104:105], v[52:53]
	v_pk_fma_f32 v[106:107], v[52:53], v[52:53], v[106:107]
	v_pk_add_f32 v[104:105], v[104:105], v[54:55]
	v_pk_fma_f32 v[106:107], v[54:55], v[54:55], v[106:107]
	v_pk_add_f32 v[104:105], v[104:105], v[48:49]
	v_pk_fma_f32 v[106:107], v[48:49], v[48:49], v[106:107]
	v_pk_add_f32 v[104:105], v[104:105], v[50:51]
	v_pk_fma_f32 v[106:107], v[50:51], v[50:51], v[106:107]
	v_add_f32_e32 v108, v104, v105
	v_add_f32_e32 v109, v106, v107
	s_nop 0
	ds_bpermute_b32 v104, v110, v108
	ds_bpermute_b32 v105, v110, v109
	s_waitcnt lgkmcnt(0)
	v_pk_add_f32 v[108:109], v[108:109], v[104:105]
	s_nop 0
	ds_bpermute_b32 v104, v111, v108
	ds_bpermute_b32 v105, v111, v109
	s_waitcnt lgkmcnt(0)
	v_pk_add_f32 v[108:109], v[108:109], v[104:105]
	ds_write_b64 v252, v[108:109] offset:4096
	s_waitcnt vmcnt(5)
	v_lshlrev_b32_e32 v80, 16, v230
	v_and_b32_e32 v81, 0xffff0000, v230
	v_lshlrev_b32_e32 v82, 16, v231
	v_and_b32_e32 v83, 0xffff0000, v231
	v_lshlrev_b32_e32 v84, 16, v232
	v_and_b32_e32 v85, 0xffff0000, v232
	v_lshlrev_b32_e32 v86, 16, v233
	v_and_b32_e32 v87, 0xffff0000, v233
	v_pk_add_f32 v[80:81], v[80:81], v[244:245] op_sel_hi:[1,0] neg_lo:[0,1] neg_hi:[0,1]
	v_pk_mul_f32 v[80:81], v[244:245], v[80:81] op_sel:[1,0]
	v_pk_fma_f32 v[80:81], v[80:81], v[120:121], v[116:117]
	v_pk_add_f32 v[44:45], v[44:45], v[80:81]
	v_pk_add_f32 v[82:83], v[82:83], v[244:245] op_sel_hi:[1,0] neg_lo:[0,1] neg_hi:[0,1]
	v_pk_mul_f32 v[82:83], v[244:245], v[82:83] op_sel:[1,0]
	v_pk_fma_f32 v[82:83], v[82:83], v[122:123], v[118:119]
	v_pk_add_f32 v[46:47], v[46:47], v[82:83]
	v_pk_add_f32 v[84:85], v[84:85], v[244:245] op_sel_hi:[1,0] neg_lo:[0,1] neg_hi:[0,1]
	v_pk_mul_f32 v[84:85], v[244:245], v[84:85] op_sel:[1,0]
	v_pk_fma_f32 v[84:85], v[84:85], v[112:113], v[124:125]
	v_pk_add_f32 v[40:41], v[40:41], v[84:85]
	v_pk_add_f32 v[86:87], v[86:87], v[244:245] op_sel_hi:[1,0] neg_lo:[0,1] neg_hi:[0,1]
	v_pk_mul_f32 v[86:87], v[244:245], v[86:87] op_sel:[1,0]
	v_pk_fma_f32 v[86:87], v[86:87], v[114:115], v[126:127]
	v_pk_add_f32 v[42:43], v[42:43], v[86:87]
	v_pk_mul_f32 v[106:107], v[44:45], v[44:45]
	v_pk_add_f32 v[104:105], v[44:45], v[46:47]
	v_pk_fma_f32 v[106:107], v[46:47], v[46:47], v[106:107]
	v_pk_add_f32 v[104:105], v[104:105], v[40:41]
	v_pk_fma_f32 v[106:107], v[40:41], v[40:41], v[106:107]
	v_pk_add_f32 v[104:105], v[104:105], v[42:43]
	v_pk_fma_f32 v[106:107], v[42:43], v[42:43], v[106:107]
	s_waitcnt vmcnt(4)
	v_lshlrev_b32_e32 v80, 16, v234
	v_and_b32_e32 v81, 0xffff0000, v234
	v_lshlrev_b32_e32 v82, 16, v235
	v_and_b32_e32 v83, 0xffff0000, v235
	v_lshlrev_b32_e32 v84, 16, v236
	v_and_b32_e32 v85, 0xffff0000, v236
	v_lshlrev_b32_e32 v86, 16, v237
	v_and_b32_e32 v87, 0xffff0000, v237
	v_pk_add_f32 v[80:81], v[80:81], v[244:245] op_sel_hi:[1,0] neg_lo:[0,1] neg_hi:[0,1]
	v_pk_mul_f32 v[80:81], v[244:245], v[80:81] op_sel:[1,0]
	v_pk_fma_f32 v[80:81], v[80:81], v[96:97], v[100:101]
	v_pk_add_f32 v[36:37], v[36:37], v[80:81]
	v_pk_add_f32 v[82:83], v[82:83], v[244:245] op_sel_hi:[1,0] neg_lo:[0,1] neg_hi:[0,1]
	v_pk_mul_f32 v[82:83], v[244:245], v[82:83] op_sel:[1,0]
	v_pk_fma_f32 v[82:83], v[82:83], v[98:99], v[102:103]
	v_pk_add_f32 v[38:39], v[38:39], v[82:83]
	v_pk_add_f32 v[84:85], v[84:85], v[244:245] op_sel_hi:[1,0] neg_lo:[0,1] neg_hi:[0,1]
	v_pk_mul_f32 v[84:85], v[244:245], v[84:85] op_sel:[1,0]
	v_pk_fma_f32 v[84:85], v[84:85], v[88:89], v[92:93]
	v_pk_add_f32 v[32:33], v[32:33], v[84:85]
	v_pk_add_f32 v[86:87], v[86:87], v[244:245] op_sel_hi:[1,0] neg_lo:[0,1] neg_hi:[0,1]
	v_pk_mul_f32 v[86:87], v[244:245], v[86:87] op_sel:[1,0]
	v_pk_fma_f32 v[86:87], v[86:87], v[90:91], v[94:95]
	v_pk_add_f32 v[34:35], v[34:35], v[86:87]
	v_pk_add_f32 v[104:105], v[104:105], v[36:37]
	v_pk_fma_f32 v[106:107], v[36:37], v[36:37], v[106:107]
	v_pk_add_f32 v[104:105], v[104:105], v[38:39]
	v_pk_fma_f32 v[106:107], v[38:39], v[38:39], v[106:107]
	v_pk_add_f32 v[104:105], v[104:105], v[32:33]
	v_pk_fma_f32 v[106:107], v[32:33], v[32:33], v[106:107]
	v_pk_add_f32 v[104:105], v[104:105], v[34:35]
	v_pk_fma_f32 v[106:107], v[34:35], v[34:35], v[106:107]
	v_add_f32_e32 v108, v104, v105
	v_add_f32_e32 v109, v106, v107
	s_nop 0
	ds_bpermute_b32 v104, v110, v108
	ds_bpermute_b32 v105, v110, v109
	s_waitcnt lgkmcnt(0)
; #define EPI_FOR_ROWS for (int ai = 0; ai < 2; ++ai) _Pragma("unroll") for (int m = 0; m < 4; ++m)
; __device__ __forceinline__ void unpack8(const u32x4 w, f32x4& a, f32x4& b) { a = (f32x4){bf_lo(w.x), bf_hi(w.x), bf_lo(w.y), bf_hi(w.y)}; b = (f32x4){bf_lo(w.z), bf_hi(w.z), bf_lo(w.w), bf_hi(w.w)}; }
;     __device__ __forceinline__ void piece(size_t row, int col, f32x4 v0, f32x4 v1, const f32x4 a0, const f32x4 a1, const f32x4 b0, const f32x4 b1, const f32x4 c0, const f32x4 c1,
;                                           float mean, float rstd, float& s, float& ss) const {
;     ...
;         if constexpr (RECOMP) { f32x4 r0, r1; unpack8(*(const u32x4*)(Tin + row * DM + col), r0, r1);
;             r0 = (r0 - mean) * rstd * a0 + b0; r1 = (r1 - mean) * rstd * a1 + b1; v0 = r0 * ALPHA + v0; v1 = r1 * ALPHA + v1;
;             if constexpr (MODE == 5) { v0 = v0 + c0; v1 = v1 + c1; } }
;     __device__ __forceinline__ void operator()(const f32x4 (&acc)[2][2][4][2], const Unit& u, int wr, int wc, int fr_, int fq_, LAS unsigned char* ldsx) const {
;     ...
;         EPI_FOR_ROWS {
;             const int rl = ai * HALF + wr * 64 + m * 16 + fr; const size_t row = (size_t)u.row0 + rl;
;             float mean = 0.f, rstd = 0.f; if constexpr (CONS) { const f32x2 st = X[rl]; mean = st.x; rstd = st.y; }
;             float s = 0.f, ss = 0.f;
; #pragma unroll
;             for (int bj = 0; bj < 2; ++bj) piece(row, colb + bj * HALF, acc[ai][bj][m][0], acc[ai][bj][m][1], av[bj][0], av[bj][1], bv[bj][0], bv[bj][1], cv[bj][0], cv[bj][1], mean, rstd, s, ss);
;             if constexpr (PROD) { s += __shfl_xor(s, 16); ss += __shfl_xor(ss, 16); s += __shfl_xor(s, 32); ss += __shfl_xor(ss, 32);
;                 if (fq == 0) st_out[row * 16 + (u.col0 >> 8) * 4 + wc] = (f32x2){s, ss}; }
;         }
	v_pk_add_f32 v[108:109], v[108:109], v[104:105]
	s_nop 0
	ds_bpermute_b32 v104, v111, v108
	ds_bpermute_b32 v105, v111, v109
	s_waitcnt lgkmcnt(0)
	v_pk_add_f32 v[108:109], v[108:109], v[104:105]
	ds_write_b64 v252, v[108:109] offset:4608
	s_waitcnt vmcnt(3)
	v_lshlrev_b32_e32 v80, 16, v210
	v_and_b32_e32 v81, 0xffff0000, v210
	v_lshlrev_b32_e32 v82, 16, v211
	v_and_b32_e32 v83, 0xffff0000, v211
	v_lshlrev_b32_e32 v84, 16, v212
	v_and_b32_e32 v85, 0xffff0000, v212
	v_lshlrev_b32_e32 v86, 16, v213
	v_and_b32_e32 v87, 0xffff0000, v213
	v_pk_add_f32 v[80:81], v[80:81], v[246:247] op_sel_hi:[1,0] neg_lo:[0,1] neg_hi:[0,1]
	v_pk_mul_f32 v[80:81], v[246:247], v[80:81] op_sel:[1,0]
	v_pk_fma_f32 v[80:81], v[80:81], v[120:121], v[116:117]
	v_pk_add_f32 v[28:29], v[28:29], v[80:81]
	v_pk_add_f32 v[82:83], v[82:83], v[246:247] op_sel_hi:[1,0] neg_lo:[0,1] neg_hi:[0,1]
	v_pk_mul_f32 v[82:83], v[246:247], v[82:83] op_sel:[1,0]
	v_pk_fma_f32 v[82:83], v[82:83], v[122:123], v[118:119]
	v_pk_add_f32 v[30:31], v[30:31], v[82:83]
	v_pk_add_f32 v[84:85], v[84:85], v[246:247] op_sel_hi:[1,0] neg_lo:[0,1] neg_hi:[0,1]
	v_pk_mul_f32 v[84:85], v[246:247], v[84:85] op_sel:[1,0]
	v_pk_fma_f32 v[84:85], v[84:85], v[112:113], v[124:125]
	v_pk_add_f32 v[24:25], v[24:25], v[84:85]
	v_pk_add_f32 v[86:87], v[86:87], v[246:247] op_sel_hi:[1,0] neg_lo:[0,1] neg_hi:[0,1]
	v_pk_mul_f32 v[86:87], v[246:247], v[86:87] op_sel:[1,0]
	v_pk_fma_f32 v[86:87], v[86:87], v[114:115], v[126:127]
	v_pk_add_f32 v[26:27], v[26:27], v[86:87]
	v_pk_mul_f32 v[106:107], v[28:29], v[28:29]
	v_pk_add_f32 v[104:105], v[28:29], v[30:31]
	v_pk_fma_f32 v[106:107], v[30:31], v[30:31], v[106:107]
	v_pk_add_f32 v[104:105], v[104:105], v[24:25]
	v_pk_fma_f32 v[106:107], v[24:25], v[24:25], v[106:107]
	v_pk_add_f32 v[104:105], v[104:105], v[26:27]
	v_pk_fma_f32 v[106:107], v[26:27], v[26:27], v[106:107]
	s_waitcnt vmcnt(2)
	v_lshlrev_b32_e32 v80, 16, v218
	v_and_b32_e32 v81, 0xffff0000, v218
	v_lshlrev_b32_e32 v82, 16, v219
	v_and_b32_e32 v83, 0xffff0000, v219
	v_lshlrev_b32_e32 v84, 16, v220
	v_and_b32_e32 v85, 0xffff0000, v220
	v_lshlrev_b32_e32 v86, 16, v221
	v_and_b32_e32 v87, 0xffff0000, v221
	v_pk_add_f32 v[80:81], v[80:81], v[246:247] op_sel_hi:[1,0] neg_lo:[0,1] neg_hi:[0,1]
	v_pk_mul_f32 v[80:81], v[246:247], v[80:81] op_sel:[1,0]
	v_pk_fma_f32 v[80:81], v[80:81], v[96:97], v[100:101]
	v_pk_add_f32 v[20:21], v[20:21], v[80:81]
	v_pk_add_f32 v[82:83], v[82:83], v[246:247] op_sel_hi:[1,0] neg_lo:[0,1] neg_hi:[0,1]
	v_pk_mul_f32 v[82:83], v[246:247], v[82:83] op_sel:[1,0]
	v_pk_fma_f32 v[82:83], v[82:83], v[98:99], v[102:103]
	v_pk_add_f32 v[22:23], v[22:23], v[82:83]
	v_pk_add_f32 v[84:85], v[84:85], v[246:247] op_sel_hi:[1,0] neg_lo:[0,1] neg_hi:[0,1]
	v_pk_mul_f32 v[84:85], v[246:247], v[84:85] op_sel:[1,0]
	v_pk_fma_f32 v[84:85], v[84:85], v[88:89], v[92:93]
	v_pk_add_f32 v[16:17], v[16:17], v[84:85]
	v_pk_add_f32 v[86:87], v[86:87], v[246:247] op_sel_hi:[1,0] neg_lo:[0,1] neg_hi:[0,1]
	v_pk_mul_f32 v[86:87], v[246:247], v[86:87] op_sel:[1,0]
	v_pk_fma_f32 v[86:87], v[86:87], v[90:91], v[94:95]
	v_pk_add_f32 v[18:19], v[18:19], v[86:87]
	v_pk_add_f32 v[104:105], v[104:105], v[20:21]
	v_pk_fma_f32 v[106:107], v[20:21], v[20:21], v[106:107]
	v_pk_add_f32 v[104:105], v[104:105], v[22:23]
	v_pk_fma_f32 v[106:107], v[22:23], v[22:23], v[106:107]
	v_pk_add_f32 v[104:105], v[104:105], v[16:17]
	v_pk_fma_f32 v[106:107], v[16:17], v[16:17], v[106:107]
	v_pk_add_f32 v[104:105], v[104:105], v[18:19]
	v_pk_fma_f32 v[106:107], v[18:19], v[18:19], v[106:107]
	v_add_f32_e32 v108, v104, v105
	v_add_f32_e32 v109, v106, v107
	s_nop 0
	ds_bpermute_b32 v104, v110, v108
	ds_bpermute_b32 v105, v110, v109
	s_waitcnt lgkmcnt(0)
	v_pk_add_f32 v[108:109], v[108:109], v[104:105]
	s_nop 0
	ds_bpermute_b32 v104, v111, v108
	ds_bpermute_b32 v105, v111, v109
	s_waitcnt lgkmcnt(0)
	v_pk_add_f32 v[108:109], v[108:109], v[104:105]
	ds_write_b64 v252, v[108:109] offset:5120
	s_waitcnt vmcnt(1)
; #define EPI_FOR_ROWS for (int ai = 0; ai < 2; ++ai) _Pragma("unroll") for (int m = 0; m < 4; ++m)
;     __device__ __forceinline__ void operator()(const f32x4 (&acc)[2][2][4][2], const Unit& u, int wr, int wc, int fr_, int fq_, LAS unsigned char* ldsx) const {
;     ...
;         EPI_FOR_ROWS {
;             const int rl = ai * HALF + wr * 64 + m * 16 + fr; const size_t row = (size_t)u.row0 + rl;
;             float mean = 0.f, rstd = 0.f; if constexpr (CONS) { const f32x2 st = X[rl]; mean = st.x; rstd = st.y; }
;             float s = 0.f, ss = 0.f;
; #pragma unroll
;             for (int bj = 0; bj < 2; ++bj) piece(row, colb + bj * HALF, acc[ai][bj][m][0], acc[ai][bj][m][1], av[bj][0], av[bj][1], bv[bj][0], bv[bj][1], cv[bj][0], cv[bj][1], mean, rstd, s, ss);
;             if constexpr (PROD) { s += __shfl_xor(s, 16); ss += __shfl_xor(ss, 16); s += __shfl_xor(s, 32); ss += __shfl_xor(ss, 32);
;                 if (fq == 0) st_out[row * 16 + (u.col0 >> 8) * 4 + wc] = (f32x2){s, ss}; }
;         }
	v_lshlrev_b32_e32 v80, 16, v222
	v_and_b32_e32 v81, 0xffff0000, v222
	v_lshlrev_b32_e32 v82, 16, v223
	v_and_b32_e32 v83, 0xffff0000, v223
	v_lshlrev_b32_e32 v84, 16, v224
	v_and_b32_e32 v85, 0xffff0000, v224
	v_lshlrev_b32_e32 v86, 16, v225
	v_and_b32_e32 v87, 0xffff0000, v225
	v_pk_add_f32 v[80:81], v[80:81], v[248:249] op_sel_hi:[1,0] neg_lo:[0,1] neg_hi:[0,1]
	v_pk_mul_f32 v[80:81], v[248:249], v[80:81] op_sel:[1,0]
	v_pk_fma_f32 v[80:81], v[80:81], v[120:121], v[116:117]
	v_pk_add_f32 v[12:13], v[12:13], v[80:81]
	v_pk_add_f32 v[82:83], v[82:83], v[248:249] op_sel_hi:[1,0] neg_lo:[0,1] neg_hi:[0,1]
	v_pk_mul_f32 v[82:83], v[248:249], v[82:83] op_sel:[1,0]
	v_pk_fma_f32 v[82:83], v[82:83], v[122:123], v[118:119]
	v_pk_add_f32 v[14:15], v[14:15], v[82:83]
	v_pk_add_f32 v[84:85], v[84:85], v[248:249] op_sel_hi:[1,0] neg_lo:[0,1] neg_hi:[0,1]
	v_pk_mul_f32 v[84:85], v[248:249], v[84:85] op_sel:[1,0]
	v_pk_fma_f32 v[84:85], v[84:85], v[112:113], v[124:125]
	v_pk_add_f32 v[8:9], v[8:9], v[84:85]
	v_pk_add_f32 v[86:87], v[86:87], v[248:249] op_sel_hi:[1,0] neg_lo:[0,1] neg_hi:[0,1]
	v_pk_mul_f32 v[86:87], v[248:249], v[86:87] op_sel:[1,0]
	v_pk_fma_f32 v[86:87], v[86:87], v[114:115], v[126:127]
	v_pk_add_f32 v[10:11], v[10:11], v[86:87]
	v_pk_mul_f32 v[106:107], v[12:13], v[12:13]
	v_pk_add_f32 v[104:105], v[12:13], v[14:15]
	v_pk_fma_f32 v[106:107], v[14:15], v[14:15], v[106:107]
	v_pk_add_f32 v[104:105], v[104:105], v[8:9]
	v_pk_fma_f32 v[106:107], v[8:9], v[8:9], v[106:107]
	v_pk_add_f32 v[104:105], v[104:105], v[10:11]
	v_pk_fma_f32 v[106:107], v[10:11], v[10:11], v[106:107]
	s_waitcnt vmcnt(0)
	v_lshlrev_b32_e32 v80, 16, v226
	v_and_b32_e32 v81, 0xffff0000, v226
	v_lshlrev_b32_e32 v82, 16, v227
	v_and_b32_e32 v83, 0xffff0000, v227
	v_lshlrev_b32_e32 v84, 16, v228
	v_and_b32_e32 v85, 0xffff0000, v228
	v_lshlrev_b32_e32 v86, 16, v229
	v_and_b32_e32 v87, 0xffff0000, v229
	v_pk_add_f32 v[80:81], v[80:81], v[248:249] op_sel_hi:[1,0] neg_lo:[0,1] neg_hi:[0,1]
	v_pk_mul_f32 v[80:81], v[248:249], v[80:81] op_sel:[1,0]
	v_pk_fma_f32 v[80:81], v[80:81], v[96:97], v[100:101]
	v_pk_add_f32 v[4:5], v[4:5], v[80:81]
	v_pk_add_f32 v[82:83], v[82:83], v[248:249] op_sel_hi:[1,0] neg_lo:[0,1] neg_hi:[0,1]
	v_pk_mul_f32 v[82:83], v[248:249], v[82:83] op_sel:[1,0]
	v_pk_fma_f32 v[82:83], v[82:83], v[98:99], v[102:103]
	v_pk_add_f32 v[6:7], v[6:7], v[82:83]
	v_pk_add_f32 v[84:85], v[84:85], v[248:249] op_sel_hi:[1,0] neg_lo:[0,1] neg_hi:[0,1]
	v_pk_mul_f32 v[84:85], v[248:249], v[84:85] op_sel:[1,0]
	v_pk_fma_f32 v[84:85], v[84:85], v[88:89], v[92:93]
	v_pk_add_f32 v[0:1], v[0:1], v[84:85]
	v_pk_add_f32 v[86:87], v[86:87], v[248:249] op_sel_hi:[1,0] neg_lo:[0,1] neg_hi:[0,1]
	v_pk_mul_f32 v[86:87], v[248:249], v[86:87] op_sel:[1,0]
	v_pk_fma_f32 v[86:87], v[86:87], v[90:91], v[94:95]
	v_pk_add_f32 v[2:3], v[2:3], v[86:87]
	v_pk_add_f32 v[104:105], v[104:105], v[4:5]
	v_pk_fma_f32 v[106:107], v[4:5], v[4:5], v[106:107]
	v_pk_add_f32 v[104:105], v[104:105], v[6:7]
	v_pk_fma_f32 v[106:107], v[6:7], v[6:7], v[106:107]
	v_pk_add_f32 v[104:105], v[104:105], v[0:1]
	v_pk_fma_f32 v[106:107], v[0:1], v[0:1], v[106:107]
	v_pk_add_f32 v[104:105], v[104:105], v[2:3]
	v_pk_fma_f32 v[106:107], v[2:3], v[2:3], v[106:107]
	v_add_f32_e32 v108, v104, v105
	v_add_f32_e32 v109, v106, v107
	s_nop 0
	ds_bpermute_b32 v104, v110, v108
	ds_bpermute_b32 v105, v110, v109
	s_waitcnt lgkmcnt(0)
	v_pk_add_f32 v[108:109], v[108:109], v[104:105]
	s_nop 0
	ds_bpermute_b32 v104, v111, v108
	ds_bpermute_b32 v105, v111, v109
	s_waitcnt lgkmcnt(0)
	v_pk_add_f32 v[108:109], v[108:109], v[104:105]
	ds_write_b64 v252, v[108:109] offset:5632
	s_waitcnt lgkmcnt(0)
	s_barrier
	s_add_u32 s98, s58, 0x1c000000
	s_addc_u32 s99, s59, 0
	v_readfirstlane_b32 s100, v202
	s_cmp_lt_u32 s100, 0x100
	s_cbranch_scc0 .Lln3_nopub
	v_lshlrev_b32_e32 v80, 5, v202
	v_add_u32_e32 v80, 0x21000, v80
	ds_read_b128 v[84:87], v80
	ds_read_b128 v[88:91], v80 offset:16
	v_add_u32_e32 v81, s20, v202
	v_lshlrev_b32_e32 v81, 5, v81
	v_mov_b32_e32 v82, s30
	v_lshrrev_b32_e32 v82, 5, v82
	v_add_u32_e32 v81, v81, v82
	s_waitcnt lgkmcnt(0)
	v_pk_add_f32 v[84:85], v[84:85], v[86:87]
	v_pk_add_f32 v[88:89], v[88:89], v[90:91]
	v_pk_add_f32 v[84:85], v[84:85], v[88:89]
	global_store_dwordx2 v81, v[84:85], s[98:99] sc0 sc1
